# speedup vs baseline: 1.0113x; 1.0113x over previous
; __device__ __forceinline__ int lane_id() { int l; asm volatile("v_mbcnt_lo_u32_b32 %0, -1, 0\n\tv_mbcnt_hi_u32_b32 %0, -1, %0" : "=v"(l)); return l; }
; #define ATT_LAS __attribute__((address_space(3)))
; __device__ __forceinline__ unsigned cvtpk(float lo, float hi) { unsigned r; asm volatile("v_cvt_pk_bf16_f32 %0, %1, %2" : "=v"(r) : "v"(lo), "v"(hi)); return r; }
; __device__ __forceinline__ void df_unit_p128(ATT_LAS unsigned char* lds, const bf16_t* Q, const bf16_t* __restrict__ K, const bf16_t* __restrict__ V, bf16_t* O, int b, int h, int qb,
;                                              float lam, float post, const float* __restrict__ sub_g, const int wv) {
;     ...
;     const float inv = (mp ? lam : 1.0f) / partner_sum(l);
;     int lane2 = lane_id(); asm volatile("" : "+v"(lane2)); const int r32e = lane2 & 31, hie = lane2 >> 5;
;     ATT_LAS f32x4* xch = (ATT_LAS f32x4*)(lds + rg * 16384) + lane2;
;     if (mp == 1) {
; #pragma unroll
;         for (int d0 = 0; d0 < 4; ++d0)
; #pragma unroll
;             for (int i = 0; i < 4; ++i) xch[(d0 * 4 + i) * 64] = (f32x4){o[d0][4 * i] * inv, o[d0][4 * i + 1] * inv, o[d0][4 * i + 2] * inv, o[d0][4 * i + 3] * inv};
;     }
;     __syncthreads();
;     if (mp == 0) {
;         float ss = 0.f;
; #pragma unroll
;         for (int d0 = 0; d0 < 4; ++d0)
; #pragma unroll
;             for (int i = 0; i < 4; ++i) { const f32x4 x2 = xch[(d0 * 4 + i) * 64];
; #pragma unroll
;                 for (int jj = 0; jj < 4; ++jj) { const float v = o[d0][4 * i + jj] * inv - x2[jj]; o[d0][4 * i + jj] = v; ss += v * v; } }
;         ss = partner_sum(ss);
;         const float rs = __builtin_amdgcn_rsqf(ss * (1.0f / 128.0f) + 1e-6f) * post;
;         bf16_t* Ow = O + (rowbase + q0 + rg * 32 + r32e) * DM + h * 128 + 4 * hie;
; #pragma unroll
;         for (int d0 = 0; d0 < 4; ++d0)
; #pragma unroll
;             for (int i = 0; i < 4; ++i) { const f32x4 g = *(const f32x4*)(sub_g + d0 * 32 + 8 * i + 4 * hie);
;                 u32x2 w; w.x = cvtpk(o[d0][4 * i] * rs * g[0], o[d0][4 * i + 1] * rs * g[1]); w.y = cvtpk(o[d0][4 * i + 2] * rs * g[2], o[d0][4 * i + 3] * rs * g[3]);
;                 *(u32x2*)(Ow + d0 * 32 + 8 * i) = w; }
.LBB0_233:
	s_andn2_b64 vcc, exec, s[8:9]
	s_waitcnt vmcnt(0) lgkmcnt(0)
	s_barrier
	s_cbranch_vccnz .LBB0_235
	ds_read_b128 v[6:9], v2
	s_waitcnt lgkmcnt(0)
	v_fma_f32 v37, v66, v0, -v6
	v_fma_f32 v34, v67, v0, -v7
	v_fma_f32 v35, v68, v0, -v8
	v_fma_f32 v36, v69, v0, -v9
	ds_read_b128 v[6:9], v2 offset:1024
	v_mul_f32_e32 v3, v34, v34
	v_fmac_f32_e32 v3, v37, v37
	v_fmac_f32_e32 v3, v35, v35
	v_fmac_f32_e32 v3, v36, v36
	s_waitcnt lgkmcnt(0)
	v_fma_f32 v50, v70, v0, -v6
	v_fma_f32 v51, v71, v0, -v7
	v_fma_f32 v52, v72, v0, -v8
	v_fma_f32 v53, v73, v0, -v9
	ds_read_b128 v[6:9], v2 offset:2048
	v_fmac_f32_e32 v3, v50, v50
	v_fmac_f32_e32 v3, v51, v51
	v_fmac_f32_e32 v3, v52, v52
	v_fmac_f32_e32 v3, v53, v53
	s_waitcnt lgkmcnt(0)
	v_fma_f32 v58, v74, v0, -v6
	v_fma_f32 v54, v75, v0, -v7
	v_fma_f32 v46, v76, v0, -v8
	v_fma_f32 v42, v77, v0, -v9
	ds_read_b128 v[6:9], v2 offset:3072
	v_fmac_f32_e32 v3, v58, v58
	v_fmac_f32_e32 v3, v54, v54
	v_fmac_f32_e32 v3, v46, v46
	v_fmac_f32_e32 v3, v42, v42
	s_waitcnt lgkmcnt(0)
	v_fma_f32 v71, v78, v0, -v6
	v_fma_f32 v68, v79, v0, -v7
	v_fma_f32 v65, v80, v0, -v8
	v_fma_f32 v62, v81, v0, -v9
	ds_read_b128 v[6:9], v2 offset:4096
	v_fmac_f32_e32 v3, v71, v71
	v_fmac_f32_e32 v3, v68, v68
	v_fmac_f32_e32 v3, v65, v65
	v_fmac_f32_e32 v3, v62, v62
	s_waitcnt lgkmcnt(0)
	v_fma_f32 v59, v82, v0, -v6
	v_fma_f32 v55, v83, v0, -v7
	v_fma_f32 v47, v84, v0, -v8
	v_fma_f32 v43, v85, v0, -v9
	ds_read_b128 v[6:9], v2 offset:5120
	v_fmac_f32_e32 v3, v59, v59
	v_fmac_f32_e32 v3, v55, v55
	v_fmac_f32_e32 v3, v47, v47
	v_fmac_f32_e32 v3, v43, v43
	s_waitcnt lgkmcnt(0)
	v_fma_f32 v72, v86, v0, -v6
	v_fma_f32 v69, v87, v0, -v7
	v_fma_f32 v66, v88, v0, -v8
	v_fma_f32 v63, v89, v0, -v9
	ds_read_b128 v[6:9], v2 offset:6144
	v_fmac_f32_e32 v3, v72, v72
	v_fmac_f32_e32 v3, v69, v69
	v_fmac_f32_e32 v3, v66, v66
	v_fmac_f32_e32 v3, v63, v63
	s_waitcnt lgkmcnt(0)
	v_fma_f32 v60, v90, v0, -v6
	v_fma_f32 v56, v91, v0, -v7
	v_fma_f32 v48, v92, v0, -v8
	v_fma_f32 v44, v93, v0, -v9
	ds_read_b128 v[6:9], v2 offset:7168
	v_fmac_f32_e32 v3, v60, v60
	v_fmac_f32_e32 v3, v56, v56
	v_fmac_f32_e32 v3, v48, v48
	v_fmac_f32_e32 v3, v44, v44
	s_waitcnt lgkmcnt(0)
	v_fma_f32 v73, v94, v0, -v6
	v_fma_f32 v70, v95, v0, -v7
	v_fma_f32 v67, v96, v0, -v8
	v_fma_f32 v64, v97, v0, -v9
	ds_read_b128 v[6:9], v2 offset:8192
	v_fmac_f32_e32 v3, v73, v73
	v_fmac_f32_e32 v3, v70, v70
	v_fmac_f32_e32 v3, v67, v67
	v_fmac_f32_e32 v3, v64, v64
	s_waitcnt lgkmcnt(0)
	v_fma_f32 v61, v98, v0, -v6
	v_fma_f32 v57, v99, v0, -v7
	v_fma_f32 v49, v100, v0, -v8
	v_fma_f32 v45, v101, v0, -v9
	ds_read_b128 v[6:9], v2 offset:9216
	v_fmac_f32_e32 v3, v61, v61
	v_fmac_f32_e32 v3, v57, v57
	v_fmac_f32_e32 v3, v49, v49
	v_fmac_f32_e32 v3, v45, v45
	s_waitcnt lgkmcnt(0)
	v_fma_f32 v41, v102, v0, -v6
	v_fma_f32 v40, v103, v0, -v7
	v_fma_f32 v39, v104, v0, -v8
	v_fma_f32 v38, v105, v0, -v9
	ds_read_b128 v[6:9], v2 offset:10240
	v_fmac_f32_e32 v3, v41, v41
	v_fmac_f32_e32 v3, v40, v40
	v_fmac_f32_e32 v3, v39, v39
	v_fmac_f32_e32 v3, v38, v38
	s_waitcnt lgkmcnt(0)
	v_fma_f32 v33, v106, v0, -v6
	v_fma_f32 v32, v107, v0, -v7
	v_fma_f32 v31, v108, v0, -v8
	v_fma_f32 v30, v109, v0, -v9
	ds_read_b128 v[6:9], v2 offset:11264
	v_fmac_f32_e32 v3, v33, v33
	v_fmac_f32_e32 v3, v32, v32
	v_fmac_f32_e32 v3, v31, v31
	v_fmac_f32_e32 v3, v30, v30
	s_waitcnt lgkmcnt(0)
	v_fma_f32 v29, v110, v0, -v6
	v_fma_f32 v28, v111, v0, -v7
	v_fma_f32 v27, v112, v0, -v8
	v_fma_f32 v26, v113, v0, -v9
	ds_read_b128 v[6:9], v2 offset:12288
	v_fmac_f32_e32 v3, v29, v29
	v_fmac_f32_e32 v3, v28, v28
	v_fmac_f32_e32 v3, v27, v27
	v_fmac_f32_e32 v3, v26, v26
	s_waitcnt lgkmcnt(0)
	v_fma_f32 v25, v114, v0, -v6
	v_fma_f32 v24, v115, v0, -v7
	v_fma_f32 v23, v116, v0, -v8
	v_fma_f32 v22, v117, v0, -v9
	ds_read_b128 v[6:9], v2 offset:13312
	v_fmac_f32_e32 v3, v25, v25
	v_fmac_f32_e32 v3, v24, v24
	v_fmac_f32_e32 v3, v23, v23
	v_fmac_f32_e32 v3, v22, v22
	s_waitcnt lgkmcnt(0)
	v_fma_f32 v21, v118, v0, -v6
	v_fma_f32 v20, v119, v0, -v7
	v_fma_f32 v19, v120, v0, -v8
	v_fma_f32 v18, v121, v0, -v9
	ds_read_b128 v[6:9], v2 offset:14336
	v_fmac_f32_e32 v3, v21, v21
	v_fmac_f32_e32 v3, v20, v20
	v_fmac_f32_e32 v3, v19, v19
	v_fmac_f32_e32 v3, v18, v18
	s_waitcnt lgkmcnt(0)
	v_fma_f32 v17, v122, v0, -v6
	v_fma_f32 v16, v123, v0, -v7
	v_fma_f32 v15, v124, v0, -v8
	v_fma_f32 v14, v125, v0, -v9
	ds_read_b128 v[6:9], v2 offset:15360
	v_fmac_f32_e32 v3, v17, v17
	v_fmac_f32_e32 v3, v16, v16
	v_fmac_f32_e32 v3, v15, v15
	v_fmac_f32_e32 v3, v14, v14
	s_waitcnt lgkmcnt(0)
	v_fma_f32 v13, v126, v0, -v6
	v_fmac_f32_e32 v3, v13, v13
	v_fma_f32 v12, v127, v0, -v7
	v_fmac_f32_e32 v3, v12, v12
	v_fma_f32 v10, v128, v0, -v8
	v_fmac_f32_e32 v3, v10, v10
	v_fma_f32 v0, v129, v0, -v9
	v_fmac_f32_e32 v3, v0, v0
	v_mov_b32_e32 v2, v3
	s_nop 1
	v_permlane32_swap_b32_e32 v3, v2
	v_add_f32_e32 v2, v3, v2
	v_fmamk_f32 v2, v2, 0x3c000000, v240
	v_rsq_f32_e32 v2, v2
	v_mov_b32_e32 v3, s27
	v_mul_f32_e32 v11, v245, v2
	v_and_or_b32 v2, v4, 31, s26
	v_ashrrev_i32_e32 v4, 3, v4
	v_lshlrev_b64 v[2:3], 11, v[2:3]
	v_and_b32_e32 v4, -4, v4
	v_lshl_add_u64 v[2:3], s[56:57], 0, v[2:3]
	v_ashrrev_i32_e32 v5, 31, v4
	v_lshl_add_u64 v[2:3], v[2:3], 0, s[54:55]
	v_lshl_add_u64 v[8:9], v[4:5], 2, s[0:1]
	v_lshl_add_u64 v[6:7], v[4:5], 1, v[2:3]
	global_load_dwordx4 v[130:133], v[8:9], off
	global_load_dwordx4 v[134:137], v[8:9], off offset:32
	global_load_dwordx4 v[138:141], v[8:9], off offset:64
	global_load_dwordx4 v[142:145], v[8:9], off offset:96
	global_load_dwordx4 v[146:149], v[8:9], off offset:128
	global_load_dwordx4 v[150:153], v[8:9], off offset:160
	global_load_dwordx4 v[154:157], v[8:9], off offset:192
	global_load_dwordx4 v[158:161], v[8:9], off offset:224
	global_load_dwordx4 v[162:165], v[8:9], off offset:256
	global_load_dwordx4 v[166:169], v[8:9], off offset:288
	global_load_dwordx4 v[170:173], v[8:9], off offset:320
	global_load_dwordx4 v[174:177], v[8:9], off offset:352
	global_load_dwordx4 v[178:181], v[8:9], off offset:384
	global_load_dwordx4 v[182:185], v[8:9], off offset:416
	global_load_dwordx4 v[186:189], v[8:9], off offset:448
	global_load_dwordx4 v[190:193], v[8:9], off offset:480
	s_nop 0
	v_mul_f32_e32 v37, v37, v11
	v_mul_f32_e32 v34, v34, v11
	v_mul_f32_e32 v33, v33, v11
	v_mul_f32_e32 v32, v32, v11
	v_mul_f32_e32 v29, v29, v11
	v_mul_f32_e32 v28, v28, v11
	v_mul_f32_e32 v25, v25, v11
	v_mul_f32_e32 v24, v24, v11
	v_mul_f32_e32 v21, v21, v11
	v_mul_f32_e32 v20, v20, v11
	v_mul_f32_e32 v17, v17, v11
	v_mul_f32_e32 v16, v16, v11
	v_mul_f32_e32 v0, v0, v11
	s_waitcnt vmcnt(0)
; __device__ __forceinline__ unsigned cvtpk(float lo, float hi) { unsigned r; asm volatile("v_cvt_pk_bf16_f32 %0, %1, %2" : "=v"(r) : "v"(lo), "v"(hi)); return r; }
; __device__ __forceinline__ void df_unit_p128(ATT_LAS unsigned char* lds, const bf16_t* Q, const bf16_t* __restrict__ K, const bf16_t* __restrict__ V, bf16_t* O, int b, int h, int qb,
;                                              float lam, float post, const float* __restrict__ sub_g, const int wv) {
;     ...
; #pragma unroll
;         for (int d0 = 0; d0 < 4; ++d0)
; #pragma unroll
;             for (int i = 0; i < 4; ++i) { const f32x4 g = *(const f32x4*)(sub_g + d0 * 32 + 8 * i + 4 * hie);
;                 u32x2 w; w.x = cvtpk(o[d0][4 * i] * rs * g[0], o[d0][4 * i + 1] * rs * g[1]); w.y = cvtpk(o[d0][4 * i + 2] * rs * g[2], o[d0][4 * i + 3] * rs * g[3]);
;                 *(u32x2*)(Ow + d0 * 32 + 8 * i) = w; }
	v_mul_f32_e32 v2, v130, v37
	v_mul_f32_e32 v3, v131, v34
	v_cvt_pk_bf16_f32 v2, v2, v3
	v_mul_f32_e32 v3, v35, v11
	v_mul_f32_e32 v3, v132, v3
	v_mul_f32_e32 v4, v36, v11
	v_mul_f32_e32 v4, v133, v4
	v_cvt_pk_bf16_f32 v3, v3, v4
	global_store_dwordx2 v[6:7], v[2:3], off
	v_mul_f32_e32 v34, v50, v11
	v_mul_f32_e32 v2, v134, v34
	v_mul_f32_e32 v34, v51, v11
	v_mul_f32_e32 v3, v135, v34
	v_cvt_pk_bf16_f32 v2, v2, v3
	v_mul_f32_e32 v3, v52, v11
	v_mul_f32_e32 v3, v136, v3
	v_mul_f32_e32 v4, v53, v11
	v_mul_f32_e32 v4, v137, v4
	v_cvt_pk_bf16_f32 v3, v3, v4
	global_store_dwordx2 v[6:7], v[2:3], off offset:16
	v_mul_f32_e32 v34, v58, v11
	v_mul_f32_e32 v2, v34, v138
	v_mul_f32_e32 v34, v54, v11
	v_mul_f32_e32 v3, v34, v139
	v_cvt_pk_bf16_f32 v2, v2, v3
	v_mul_f32_e32 v3, v46, v11
	v_mul_f32_e32 v3, v3, v140
	v_mul_f32_e32 v4, v42, v11
	v_mul_f32_e32 v4, v4, v141
	v_cvt_pk_bf16_f32 v3, v3, v4
	global_store_dwordx2 v[6:7], v[2:3], off offset:32
	v_mul_f32_e32 v34, v71, v11
	v_mul_f32_e32 v2, v34, v142
	v_mul_f32_e32 v34, v68, v11
	v_mul_f32_e32 v3, v34, v143
	v_cvt_pk_bf16_f32 v2, v2, v3
	v_mul_f32_e32 v3, v65, v11
	v_mul_f32_e32 v3, v3, v144
	v_mul_f32_e32 v4, v62, v11
	v_mul_f32_e32 v4, v4, v145
	v_cvt_pk_bf16_f32 v3, v3, v4
	global_store_dwordx2 v[6:7], v[2:3], off offset:48
	v_mul_f32_e32 v34, v59, v11
	v_mul_f32_e32 v2, v34, v146
	v_mul_f32_e32 v34, v55, v11
	v_mul_f32_e32 v3, v34, v147
	v_cvt_pk_bf16_f32 v2, v2, v3
	v_mul_f32_e32 v3, v47, v11
	v_mul_f32_e32 v3, v3, v148
	v_mul_f32_e32 v4, v43, v11
	v_mul_f32_e32 v4, v4, v149
	v_cvt_pk_bf16_f32 v3, v3, v4
	global_store_dwordx2 v[6:7], v[2:3], off offset:64
	v_mul_f32_e32 v34, v72, v11
	v_mul_f32_e32 v2, v34, v150
	v_mul_f32_e32 v34, v69, v11
	v_mul_f32_e32 v3, v34, v151
	v_cvt_pk_bf16_f32 v2, v2, v3
	v_mul_f32_e32 v3, v66, v11
	v_mul_f32_e32 v3, v3, v152
	v_mul_f32_e32 v4, v63, v11
	v_mul_f32_e32 v4, v4, v153
	v_cvt_pk_bf16_f32 v3, v3, v4
	global_store_dwordx2 v[6:7], v[2:3], off offset:80
	v_mul_f32_e32 v34, v60, v11
	v_mul_f32_e32 v2, v34, v154
	v_mul_f32_e32 v34, v56, v11
	v_mul_f32_e32 v3, v34, v155
	v_cvt_pk_bf16_f32 v2, v2, v3
	v_mul_f32_e32 v3, v48, v11
	v_mul_f32_e32 v3, v3, v156
	v_mul_f32_e32 v4, v44, v11
	v_mul_f32_e32 v4, v4, v157
	v_cvt_pk_bf16_f32 v3, v3, v4
	global_store_dwordx2 v[6:7], v[2:3], off offset:96
	v_mul_f32_e32 v34, v73, v11
	v_mul_f32_e32 v2, v34, v158
	v_mul_f32_e32 v34, v70, v11
	v_mul_f32_e32 v3, v34, v159
	v_cvt_pk_bf16_f32 v2, v2, v3
	v_mul_f32_e32 v3, v67, v11
	v_mul_f32_e32 v3, v3, v160
	v_mul_f32_e32 v4, v64, v11
	v_mul_f32_e32 v4, v4, v161
	v_cvt_pk_bf16_f32 v3, v3, v4
	global_store_dwordx2 v[6:7], v[2:3], off offset:112
	v_mul_f32_e32 v34, v61, v11
	v_mul_f32_e32 v2, v34, v162
	v_mul_f32_e32 v34, v57, v11
	v_mul_f32_e32 v3, v34, v163
	v_cvt_pk_bf16_f32 v2, v2, v3
	v_mul_f32_e32 v3, v49, v11
	v_mul_f32_e32 v3, v3, v164
	v_mul_f32_e32 v4, v45, v11
	v_mul_f32_e32 v4, v4, v165
	v_cvt_pk_bf16_f32 v3, v3, v4
	global_store_dwordx2 v[6:7], v[2:3], off offset:128
	v_mul_f32_e32 v34, v41, v11
	v_mul_f32_e32 v2, v34, v166
	v_mul_f32_e32 v34, v40, v11
	v_mul_f32_e32 v3, v34, v167
	v_cvt_pk_bf16_f32 v2, v2, v3
	v_mul_f32_e32 v3, v39, v11
	v_mul_f32_e32 v3, v3, v168
	v_mul_f32_e32 v4, v38, v11
	v_mul_f32_e32 v4, v4, v169
	v_cvt_pk_bf16_f32 v3, v3, v4
	global_store_dwordx2 v[6:7], v[2:3], off offset:144
	v_mul_f32_e32 v2, v33, v170
	v_mul_f32_e32 v3, v32, v171
	v_cvt_pk_bf16_f32 v2, v2, v3
	v_mul_f32_e32 v3, v31, v11
	v_mul_f32_e32 v3, v3, v172
	v_mul_f32_e32 v4, v30, v11
	v_mul_f32_e32 v4, v4, v173
	v_cvt_pk_bf16_f32 v3, v3, v4
	global_store_dwordx2 v[6:7], v[2:3], off offset:160
	v_mul_f32_e32 v2, v29, v174
	v_mul_f32_e32 v3, v28, v175
	v_cvt_pk_bf16_f32 v2, v2, v3
	v_mul_f32_e32 v3, v27, v11
	v_mul_f32_e32 v3, v3, v176
	v_mul_f32_e32 v4, v26, v11
	v_mul_f32_e32 v4, v4, v177
	v_cvt_pk_bf16_f32 v3, v3, v4
	global_store_dwordx2 v[6:7], v[2:3], off offset:176
	v_mul_f32_e32 v2, v25, v178
	v_mul_f32_e32 v3, v24, v179
	v_cvt_pk_bf16_f32 v2, v2, v3
	v_mul_f32_e32 v3, v23, v11
	v_mul_f32_e32 v3, v3, v180
	v_mul_f32_e32 v4, v22, v11
	v_mul_f32_e32 v4, v4, v181
	v_cvt_pk_bf16_f32 v3, v3, v4
	global_store_dwordx2 v[6:7], v[2:3], off offset:192
	v_mul_f32_e32 v2, v21, v182
	v_mul_f32_e32 v3, v20, v183
	v_cvt_pk_bf16_f32 v2, v2, v3
	v_mul_f32_e32 v3, v19, v11
	v_mul_f32_e32 v3, v3, v184
	v_mul_f32_e32 v4, v18, v11
	v_mul_f32_e32 v4, v4, v185
	v_cvt_pk_bf16_f32 v3, v3, v4
	global_store_dwordx2 v[6:7], v[2:3], off offset:208
	v_mul_f32_e32 v2, v17, v186
	v_mul_f32_e32 v3, v16, v187
	v_cvt_pk_bf16_f32 v2, v2, v3
	v_mul_f32_e32 v3, v15, v11
	v_mul_f32_e32 v3, v3, v188
	v_mul_f32_e32 v4, v14, v11
	v_mul_f32_e32 v4, v4, v189
	v_cvt_pk_bf16_f32 v3, v3, v4
	global_store_dwordx2 v[6:7], v[2:3], off offset:224
	v_mul_f32_e32 v8, v13, v11
	v_mul_f32_e32 v2, v8, v190
	v_mul_f32_e32 v8, v12, v11
	v_mul_f32_e32 v3, v8, v191
	v_cvt_pk_bf16_f32 v2, v2, v3
	v_mul_f32_e32 v3, v10, v11
	v_mul_f32_e32 v3, v3, v192
	v_mul_f32_e32 v0, v0, v193
	v_cvt_pk_bf16_f32 v3, v3, v0
	global_store_dwordx2 v[6:7], v[2:3], off offset:240
